# v9 plus fp8 conversion of the PEER up tables moved from prep into the idle tails of the two projection phases
# speedup vs baseline: 1.0339x; 1.0339x over previous
.LBB0_55:
	s_or_b64 exec, exec, s[22:23]
.LBB0_58:
	s_or_b64 exec, exec, s[10:11]
	s_mov_b32 s9, 0
	s_mov_b32 s89, s9
	s_lshl_b64 s[0:1], s[88:89], 9
	v_lshl_add_u64 v[0:1], s[0:1], 0, v[16:17]
	s_mov_b64 s[0:1], 0xfff
	v_cmp_lt_u64_e32 vcc, s[0:1], v[0:1]
	s_and_saveexec_b64 s[0:1], vcc
	s_xor_b64 s[0:1], exec, s[0:1]
	s_andn2_saveexec_b64 s[0:1], s[0:1]
	s_cbranch_execz .LBB0_66
	s_lshl_b64 s[10:11], s[8:9], 9
	s_lshl_b64 s[12:13], s[88:89], 13
	s_add_u32 s2, s2, s12
	s_addc_u32 s3, s3, s13
	v_lshl_add_u64 v[2:3], v[16:17], 4, s[2:3]
	v_readlane_b32 s2, v254, 0
	s_lshl_b64 s[12:13], s[88:89], 14
	v_lshlrev_b64 v[6:7], 5, v[16:17]
	v_readlane_b32 s3, v254, 1
	v_lshl_add_u64 v[6:7], s[12:13], 0, v[6:7]
	v_lshl_add_u64 v[6:7], s[60:61], 0, v[6:7]
	v_lshl_add_u64 v[2:3], s[2:3], 0, v[2:3]
	s_mov_b64 s[2:3], 0x2100008
	v_lshl_add_u64 v[4:5], v[2:3], 0, s[2:3]
	s_lshl_b64 s[2:3], s[8:9], 13
	v_lshl_add_u64 v[8:9], v[6:7], 0, 16
	s_lshl_b64 s[12:13], s[8:9], 14
	s_mov_b64 s[14:15], 0
	s_mov_b64 s[16:17], 0xfff
	v_mov_b64_e32 v[10:11], v[0:1]

.LBB0_184:
	v_and_b32_e32 v10, 0x3f0, v12
	v_lshlrev_b32_e32 v10, 2, v10
	global_load_dwordx4 v[18:21], v[8:9], off offset:32
	global_load_dwordx4 v[22:25], v[8:9], off offset:16
	global_load_dwordx4 v[26:29], v[8:9], off
	global_load_dwordx4 v[30:33], v10, s[12:13]
	global_load_dwordx4 v[34:37], v10, s[12:13] offset:16
	global_load_dwordx4 v[38:41], v10, s[12:13] offset:32
	global_load_dwordx4 v[42:45], v10, s[12:13] offset:48
	global_load_dwordx4 v[46:49], v[8:9], off offset:48
	v_mov_b32_e32 v50, 0
	v_mov_b32_e32 v51, 0
	v_mov_b32_e32 v52, 0
	v_mov_b32_e32 v53, 0
	v_lshrrev_b64 v[54:55], 6, v[16:17]
	v_and_b32_e32 v56, 0x1c000, v14
	v_or_b32_e32 v54, v56, v54
	v_lshl_add_u64 v[16:17], v[16:17], 0, s[2:3]
	v_lshlrev_b64 v[54:55], 7, v[54:55]
	v_and_b32_e32 v10, 0x70, v12
	v_cmp_lt_u64_e32 vcc, s[16:17], v[16:17]
	v_lshl_add_u64 v[14:15], v[14:15], 0, s[4:5]
	v_lshl_add_u64 v[8:9], v[8:9], 0, s[6:7]
	v_lshl_add_u64 v[12:13], v[12:13], 0, s[8:9]
	s_or_b64 s[14:15], vcc, s[14:15]
	s_waitcnt vmcnt(4)
	v_mul_f32_e32 v30, 0x42800000, v30
	v_mul_f32_e32 v31, 0x42800000, v31
	s_waitcnt vmcnt(3)
	v_mul_f32_e32 v34, 0x42800000, v34
	v_mul_f32_e32 v35, 0x42800000, v35
	s_waitcnt vmcnt(2)
	v_mul_f32_e32 v38, 0x42800000, v38
	v_mul_f32_e32 v39, 0x42800000, v39
	s_waitcnt vmcnt(1)
	v_mul_f32_e32 v42, 0x42800000, v42
	v_mul_f32_e32 v43, 0x42800000, v43
	v_mul_f32_e32 v26, v26, v30
	v_mul_f32_e32 v27, v27, v31
	v_mul_f32_e32 v22, v22, v34
	v_mul_f32_e32 v23, v23, v35
	v_mul_f32_e32 v18, v18, v38
	v_mul_f32_e32 v19, v19, v39
	s_waitcnt vmcnt(0)
	v_mul_f32_e32 v30, v46, v42
	v_mul_f32_e32 v31, v47, v43
	v_cvt_pk_fp8_f32 v50, v26, v27
	v_cvt_pk_fp8_f32 v51, v22, v23
	v_cvt_pk_fp8_f32 v52, v18, v19
	v_cvt_pk_fp8_f32 v53, v30, v31
	v_mul_f32_e32 v32, 0x42800000, v32
	v_mul_f32_e32 v33, 0x42800000, v33
	v_mul_f32_e32 v36, 0x42800000, v36
	v_mul_f32_e32 v37, 0x42800000, v37
	v_mul_f32_e32 v40, 0x42800000, v40
	v_mul_f32_e32 v41, 0x42800000, v41
	v_mul_f32_e32 v44, 0x42800000, v44
	v_mul_f32_e32 v45, 0x42800000, v45
	v_mul_f32_e32 v28, v28, v32
	v_mul_f32_e32 v29, v29, v33
	v_mul_f32_e32 v24, v24, v36
	v_mul_f32_e32 v25, v25, v37
	v_mul_f32_e32 v20, v20, v40
	v_mul_f32_e32 v21, v21, v41
	v_mul_f32_e32 v32, v48, v44
	v_mul_f32_e32 v33, v49, v45
	v_cvt_pk_fp8_f32 v50, v28, v29 op_sel:[0,0,1]
	v_cvt_pk_fp8_f32 v51, v24, v25 op_sel:[0,0,1]
	v_cvt_pk_fp8_f32 v52, v20, v21 op_sel:[0,0,1]
	v_cvt_pk_fp8_f32 v53, v32, v33 op_sel:[0,0,1]
	v_lshl_add_u64 v[18:19], s[10:11], 0, v[54:55]
	v_lshl_add_u64 v[18:19], v[18:19], 0, v[10:11]
	global_store_dwordx4 v[18:19], v[50:53], off
	s_andn2_b64 exec, exec, s[14:15]
	s_cbranch_execnz .LBB0_184
	s_or_b64 exec, exec, s[14:15]
	s_add_u32 s10, s21, 0x6120000
	s_addc_u32 s11, s33, 0
	v_lshl_add_u64 v[6:7], s[68:69], 0, v[6:7]
	s_mov_b32 s12, 0xfc000000
	s_mov_b32 s13, -1
	v_lshl_add_u64 v[6:7], v[6:7], 0, s[12:13]
	s_mov_b64 s[12:13], 0
	v_mov_b32_e32 v9, 0
	s_mov_b64 s[14:15], 0xfffff

.LBB0_774:
	s_abs_i32 s0, s90
	v_cvt_f32_u32_e32 v0, s0
	s_sub_i32 s1, 0, s0
	s_mov_b32 s9, 0
	v_rcp_iflag_f32_e32 v0, v0
	s_nop 1
	v_mul_f32_e32 v0, 0x4f7ffffe, v0
	v_cvt_u32_f32_e32 v0, v0
	s_nop 1
	v_readfirstlane_b32 s2, v0
	s_mul_i32 s1, s1, s2
	s_mul_hi_u32 s1, s2, s1
	s_add_i32 s2, s2, s1
	s_mul_hi_u32 s1, s2, 0x43f
	s_mul_i32 s1, s1, s0
	s_sub_i32 s1, 0x43f, s1
	s_sub_i32 s2, s1, s0
	s_cmp_ge_u32 s1, s0
	s_cselect_b32 s1, s2, s1
	s_sub_i32 s2, s1, s0
	s_cmp_ge_u32 s1, s0
	s_cselect_b32 s0, s2, s1
	s_add_i32 s5, s0, 1
	s_sub_i32 s4, s90, s5
	s_cmp_lt_i32 s4, 1
	s_cselect_b64 s[2:3], -1, 0
	s_and_b64 s[0:1], s[2:3], exec
	s_cselect_b32 s0, 0, s5
	s_sub_i32 s8, s88, s0
	s_cmp_gt_i32 s8, -1
	s_cbranch_scc0 .Lt1_skip
	v_readlane_b32 s68, v254, 37
	v_readlane_b32 s69, v254, 38
	v_readlane_b32 s20, v254, 0
	v_readlane_b32 s21, v254, 1
	s_lshl_b64 s[0:1], s[8:9], 9
	v_mov_b32_e32 v20, v178
	v_mov_b32_e32 v21, 0
	v_lshl_add_u64 v[0:1], s[0:1], 0, v[20:21]
	s_mov_b64 s[26:27], 0x100000
	v_cmp_gt_u64_e32 vcc, s[26:27], v[0:1]
	s_and_saveexec_b64 s[0:1], vcc
	s_cbranch_execz .Lt1_end
	s_and_b64 s[2:3], s[2:3], exec
	s_cselect_b32 s22, s90, s4
	s_lshl_b64 s[6:7], s[8:9], 15
	v_lshlrev_b64 v[4:5], 6, v[20:21]
	s_lshl_b64 s[4:5], s[8:9], 20
	v_lshlrev_b64 v[2:3], 11, v[20:21]
	v_lshl_add_u64 v[4:5], s[6:7], 0, v[4:5]
	s_mov_b64 s[6:7], 0x4000000
	s_lshl_b64 s[8:9], s[8:9], 13
	s_ashr_i32 s23, s22, 31
	v_lshl_add_u64 v[2:3], s[4:5], 0, v[2:3]
	v_lshl_add_u64 v[6:7], v[4:5], 0, s[6:7]
	v_lshl_add_u64 v[4:5], v[20:21], 4, s[8:9]
	s_lshl_b64 s[2:3], s[22:23], 9
	s_lshl_b64 s[4:5], s[22:23], 20
	s_lshl_b64 s[6:7], s[22:23], 15
	s_lshl_b64 s[8:9], s[22:23], 13
	s_add_u32 s10, s20, 0x8120000
	s_addc_u32 s11, s21, 0
	v_lshl_add_u64 v[6:7], s[68:69], 0, v[6:7]
	s_mov_b64 s[12:13], 0
	v_mov_b32_e32 v9, 0
	s_mov_b64 s[24:25], 0xfffff
.Lt1_loop:
	global_load_dwordx4 v[10:13], v[6:7], off
	global_load_dwordx4 v[14:17], v[6:7], off offset:16
	global_load_dwordx4 v[18:21], v[6:7], off offset:32
	global_load_dwordx4 v[22:25], v[6:7], off offset:48
	v_mov_b32_e32 v26, 0
	v_mov_b32_e32 v27, 0
	v_mov_b32_e32 v28, 0
	v_mov_b32_e32 v29, 0
	v_lshrrev_b64 v[30:31], 6, v[0:1]
	v_and_b32_e32 v32, 0x1c000, v2
	v_or_b32_e32 v30, v32, v30
	v_lshl_add_u64 v[0:1], v[0:1], 0, s[2:3]
	v_lshlrev_b64 v[30:31], 7, v[30:31]
	v_and_b32_e32 v8, 0x70, v4
	v_cmp_lt_u64_e32 vcc, s[24:25], v[0:1]
	v_lshl_add_u64 v[2:3], v[2:3], 0, s[4:5]
	v_lshl_add_u64 v[6:7], v[6:7], 0, s[6:7]
	v_lshl_add_u64 v[4:5], v[4:5], 0, s[8:9]
	s_or_b64 s[12:13], vcc, s[12:13]
	s_waitcnt vmcnt(3)
	v_mul_f32_e32 v10, 0x41800000, v10
	v_mul_f32_e32 v11, 0x41800000, v11
	s_waitcnt vmcnt(2)
	v_mul_f32_e32 v14, 0x41800000, v14
	v_mul_f32_e32 v15, 0x41800000, v15
	s_waitcnt vmcnt(1)
	v_mul_f32_e32 v18, 0x41800000, v18
	v_mul_f32_e32 v19, 0x41800000, v19
	s_waitcnt vmcnt(0)
	v_mul_f32_e32 v22, 0x41800000, v22
	v_mul_f32_e32 v23, 0x41800000, v23
	v_cvt_pk_fp8_f32 v26, v10, v11
	v_cvt_pk_fp8_f32 v27, v14, v15
	v_cvt_pk_fp8_f32 v28, v18, v19
	v_cvt_pk_fp8_f32 v29, v22, v23
	v_mul_f32_e32 v12, 0x41800000, v12
	v_mul_f32_e32 v13, 0x41800000, v13
	v_mul_f32_e32 v16, 0x41800000, v16
	v_mul_f32_e32 v17, 0x41800000, v17
	v_mul_f32_e32 v20, 0x41800000, v20
	v_mul_f32_e32 v21, 0x41800000, v21
	v_mul_f32_e32 v24, 0x41800000, v24
	v_mul_f32_e32 v25, 0x41800000, v25
	v_cvt_pk_fp8_f32 v26, v12, v13 op_sel:[0,0,1]
	v_cvt_pk_fp8_f32 v27, v16, v17 op_sel:[0,0,1]
	v_cvt_pk_fp8_f32 v28, v20, v21 op_sel:[0,0,1]
	v_cvt_pk_fp8_f32 v29, v24, v25 op_sel:[0,0,1]
	v_lshl_add_u64 v[10:11], s[10:11], 0, v[30:31]
	v_lshl_add_u64 v[10:11], v[10:11], 0, v[8:9]
	global_store_dwordx4 v[10:11], v[26:29], off
	s_andn2_b64 exec, exec, s[12:13]
	s_cbranch_execnz .Lt1_loop
	s_or_b64 exec, exec, s[12:13]
